# grid barrier: the workgroup completing the cross-XCD level bumps all per-XCD release words itself (XCD leaders no longer forward the release)
# baseline (speedup 1.0000x reference)
.LBB0_179:
	s_or_b64 exec, exec, s[10:11]
	s_and_saveexec_b64 s[10:11], s[14:15]
	s_cbranch_execz .LBB0_181
	v_mov_b32_e32 v1, 1
	global_atomic_add v[2:3], v1, off
	v_mov_b32_e32 v4, 0x3000
	global_atomic_add v4, v1, s[80:81] offset:1024
	v_mov_b32_e32 v4, 0x3100
	global_atomic_add v4, v1, s[80:81] offset:1024
	v_mov_b32_e32 v4, 0x3200
	global_atomic_add v4, v1, s[80:81] offset:1024
	v_mov_b32_e32 v4, 0x3300
	global_atomic_add v4, v1, s[80:81] offset:1024
	v_mov_b32_e32 v4, 0x3400
	global_atomic_add v4, v1, s[80:81] offset:1024
	v_mov_b32_e32 v4, 0x3500
	global_atomic_add v4, v1, s[80:81] offset:1024
	v_mov_b32_e32 v4, 0x3600
	global_atomic_add v4, v1, s[80:81] offset:1024
	v_mov_b32_e32 v4, 0x3700
	global_atomic_add v4, v1, s[80:81] offset:1024
	v_mov_b32_e32 v4, 0x3800
	global_atomic_add v4, v1, s[80:81] offset:1024
	v_mov_b32_e32 v4, 0x3900
	global_atomic_add v4, v1, s[80:81] offset:1024
	v_mov_b32_e32 v4, 0x3a00
	global_atomic_add v4, v1, s[80:81] offset:1024
	v_mov_b32_e32 v4, 0x3b00
	global_atomic_add v4, v1, s[80:81] offset:1024
	v_mov_b32_e32 v4, 0x3c00
	global_atomic_add v4, v1, s[80:81] offset:1024
	v_mov_b32_e32 v4, 0x3d00
	global_atomic_add v4, v1, s[80:81] offset:1024
	v_mov_b32_e32 v4, 0x3e00
	global_atomic_add v4, v1, s[80:81] offset:1024
	v_mov_b32_e32 v4, 0x3f00
	global_atomic_add v4, v1, s[80:81] offset:1024
.LBB0_181:
	s_or_b64 exec, exec, s[10:11]
	s_mov_b64 s[10:11], exec
	v_mbcnt_lo_u32_b32 v1, s10, 0
	v_mbcnt_hi_u32_b32 v1, s11, v1
	v_cmp_eq_u32_e32 vcc, 0, v1
	s_waitcnt vmcnt(0)
	buffer_inv sc1
	s_and_saveexec_b64 s[12:13], vcc
	s_cbranch_execz .LBB0_183
	s_bcnt1_i32_b64 s2, s[10:11]
	v_mov_b32_e32 v1, 0x2000
	v_mov_b32_e32 v2, s2
	s_nop 0

.LBB0_334:
	s_or_b64 exec, exec, s[8:9]
	s_and_saveexec_b64 s[8:9], s[12:13]
	s_cbranch_execz .LBB0_336
	v_mov_b32_e32 v1, 1
	global_atomic_add v[2:3], v1, off
	v_mov_b32_e32 v4, 0x3000
	global_atomic_add v4, v1, s[80:81] offset:1024
	v_mov_b32_e32 v4, 0x3100
	global_atomic_add v4, v1, s[80:81] offset:1024
	v_mov_b32_e32 v4, 0x3200
	global_atomic_add v4, v1, s[80:81] offset:1024
	v_mov_b32_e32 v4, 0x3300
	global_atomic_add v4, v1, s[80:81] offset:1024
	v_mov_b32_e32 v4, 0x3400
	global_atomic_add v4, v1, s[80:81] offset:1024
	v_mov_b32_e32 v4, 0x3500
	global_atomic_add v4, v1, s[80:81] offset:1024
	v_mov_b32_e32 v4, 0x3600
	global_atomic_add v4, v1, s[80:81] offset:1024
	v_mov_b32_e32 v4, 0x3700
	global_atomic_add v4, v1, s[80:81] offset:1024
	v_mov_b32_e32 v4, 0x3800
	global_atomic_add v4, v1, s[80:81] offset:1024
	v_mov_b32_e32 v4, 0x3900
	global_atomic_add v4, v1, s[80:81] offset:1024
	v_mov_b32_e32 v4, 0x3a00
	global_atomic_add v4, v1, s[80:81] offset:1024
	v_mov_b32_e32 v4, 0x3b00
	global_atomic_add v4, v1, s[80:81] offset:1024
	v_mov_b32_e32 v4, 0x3c00
	global_atomic_add v4, v1, s[80:81] offset:1024
	v_mov_b32_e32 v4, 0x3d00
	global_atomic_add v4, v1, s[80:81] offset:1024
	v_mov_b32_e32 v4, 0x3e00
	global_atomic_add v4, v1, s[80:81] offset:1024
	v_mov_b32_e32 v4, 0x3f00
	global_atomic_add v4, v1, s[80:81] offset:1024
.LBB0_336:
	s_or_b64 exec, exec, s[8:9]
	s_mov_b64 s[8:9], exec
	v_mbcnt_lo_u32_b32 v1, s8, 0
	v_mbcnt_hi_u32_b32 v1, s9, v1
	v_cmp_eq_u32_e32 vcc, 0, v1
	s_waitcnt vmcnt(0)
	buffer_inv sc1
	s_and_saveexec_b64 s[10:11], vcc
	s_cbranch_execz .LBB0_338
	s_bcnt1_i32_b64 s2, s[8:9]
	v_mov_b32_e32 v1, 0x2000
	v_mov_b32_e32 v2, s2
	s_nop 0
